# phase2 pool-window loader: 15 predicated loads in flight + single wait instead of a serialized load-wait loop
# speedup vs baseline: 1.1561x; 1.0174x over previous
.LBB0_266:
	s_or_saveexec_b64 s[0:1], s[0:1]
	v_mov_b32_e32 v2, v38
	s_xor_b64 exec, exec, s[0:1]
	s_cbranch_execz .LBB0_257
	v_bfe_u32 v0, v0, 6, 11
	v_cmp_ne_u32_e32 vcc, 0, v0
	v_mov_b32_e32 v2, 1
	v_mov_b32_e32 v29, v21
	v_mov_b32_e32 v28, v20
	v_mov_b32_e32 v31, v23
	v_mov_b32_e32 v30, v22
	v_mov_b32_e32 v33, v25
	v_mov_b32_e32 v32, v24
	v_mov_b32_e32 v35, v27
	v_mov_b32_e32 v34, v26
	s_and_saveexec_b64 s[4:5], vcc
	s_cbranch_execz .LBB0_256
	v_add_u32_e32 v0, 1, v0
	v_mad_i64_i32 v[4:5], s[6:7], v18, s3, 0
	v_min_u32_e32 v2, v0, v38
	v_add_u32_e32 v3, -1, v2
	v_lshl_add_u64 v[0:1], v[16:17], 0, v[4:5]
	s_mov_b64 s[6:7], exec
	s_movk_i32 s10, 0xee00
	s_mov_b32 s11, -1
	global_load_dwordx4 v[44:47], v[0:1], off
	v_cmp_lt_u32_e32 vcc, 2, v2
	s_and_b64 exec, exec, vcc
	v_lshl_add_u64 v[0:1], v[0:1], 0, s[10:11]
	global_load_dwordx4 v[48:51], v[0:1], off
	v_cmp_lt_u32_e32 vcc, 3, v2
	s_and_b64 exec, exec, vcc
	v_lshl_add_u64 v[0:1], v[0:1], 0, s[10:11]
	global_load_dwordx4 v[52:55], v[0:1], off
	v_cmp_lt_u32_e32 vcc, 4, v2
	s_and_b64 exec, exec, vcc
	v_lshl_add_u64 v[0:1], v[0:1], 0, s[10:11]
	global_load_dwordx4 v[56:59], v[0:1], off
	v_cmp_lt_u32_e32 vcc, 5, v2
	s_and_b64 exec, exec, vcc
	v_lshl_add_u64 v[0:1], v[0:1], 0, s[10:11]
	global_load_dwordx4 v[60:63], v[0:1], off
	v_cmp_lt_u32_e32 vcc, 6, v2
	s_and_b64 exec, exec, vcc
	v_lshl_add_u64 v[0:1], v[0:1], 0, s[10:11]
	global_load_dwordx4 v[64:67], v[0:1], off
	v_cmp_lt_u32_e32 vcc, 7, v2
	s_and_b64 exec, exec, vcc
	v_lshl_add_u64 v[0:1], v[0:1], 0, s[10:11]
	global_load_dwordx4 v[68:71], v[0:1], off
	v_cmp_lt_u32_e32 vcc, 8, v2
	s_and_b64 exec, exec, vcc
	v_lshl_add_u64 v[0:1], v[0:1], 0, s[10:11]
	global_load_dwordx4 v[72:75], v[0:1], off
	v_cmp_lt_u32_e32 vcc, 9, v2
	s_and_b64 exec, exec, vcc
	v_lshl_add_u64 v[0:1], v[0:1], 0, s[10:11]
	global_load_dwordx4 v[76:79], v[0:1], off
	v_cmp_lt_u32_e32 vcc, 10, v2
	s_and_b64 exec, exec, vcc
	v_lshl_add_u64 v[0:1], v[0:1], 0, s[10:11]
	global_load_dwordx4 v[80:83], v[0:1], off
	v_cmp_lt_u32_e32 vcc, 11, v2
	s_and_b64 exec, exec, vcc
	v_lshl_add_u64 v[0:1], v[0:1], 0, s[10:11]
	global_load_dwordx4 v[84:87], v[0:1], off
	v_cmp_lt_u32_e32 vcc, 12, v2
	s_and_b64 exec, exec, vcc
	v_lshl_add_u64 v[0:1], v[0:1], 0, s[10:11]
	global_load_dwordx4 v[88:91], v[0:1], off
	v_cmp_lt_u32_e32 vcc, 13, v2
	s_and_b64 exec, exec, vcc
	v_lshl_add_u64 v[0:1], v[0:1], 0, s[10:11]
	global_load_dwordx4 v[92:95], v[0:1], off
	v_cmp_lt_u32_e32 vcc, 14, v2
	s_and_b64 exec, exec, vcc
	v_lshl_add_u64 v[0:1], v[0:1], 0, s[10:11]
	global_load_dwordx4 v[96:99], v[0:1], off
	v_cmp_lt_u32_e32 vcc, 15, v2
	s_and_b64 exec, exec, vcc
	v_lshl_add_u64 v[0:1], v[0:1], 0, s[10:11]
	global_load_dwordx4 v[100:103], v[0:1], off
	s_mov_b64 exec, s[6:7]
	s_waitcnt vmcnt(0)
	v_lshlrev_b32_e32 v36, 16, v44
	v_and_b32_e32 v37, 0xffff0000, v44
	v_lshlrev_b32_e32 v4, 16, v45
	v_and_b32_e32 v5, 0xffff0000, v45
	v_lshlrev_b32_e32 v40, 16, v46
	v_and_b32_e32 v41, 0xffff0000, v46
	v_lshlrev_b32_e32 v6, 16, v47
	v_and_b32_e32 v7, 0xffff0000, v47
	v_pk_add_f32 v[28:29], v[28:29], v[6:7]
	v_pk_add_f32 v[30:31], v[30:31], v[40:41]
	v_pk_add_f32 v[32:33], v[32:33], v[4:5]
	v_pk_add_f32 v[34:35], v[34:35], v[36:37]
	v_cmp_lt_u32_e32 vcc, 2, v2
	s_and_b64 exec, exec, vcc
	v_lshlrev_b32_e32 v36, 16, v48
	v_and_b32_e32 v37, 0xffff0000, v48
	v_lshlrev_b32_e32 v4, 16, v49
	v_and_b32_e32 v5, 0xffff0000, v49
	v_lshlrev_b32_e32 v40, 16, v50
	v_and_b32_e32 v41, 0xffff0000, v50
	v_lshlrev_b32_e32 v6, 16, v51
	v_and_b32_e32 v7, 0xffff0000, v51
	v_pk_add_f32 v[28:29], v[28:29], v[6:7]
	v_pk_add_f32 v[30:31], v[30:31], v[40:41]
	v_pk_add_f32 v[32:33], v[32:33], v[4:5]
	v_pk_add_f32 v[34:35], v[34:35], v[36:37]
	v_cmp_lt_u32_e32 vcc, 3, v2
	s_and_b64 exec, exec, vcc
	v_lshlrev_b32_e32 v36, 16, v52
	v_and_b32_e32 v37, 0xffff0000, v52
	v_lshlrev_b32_e32 v4, 16, v53
	v_and_b32_e32 v5, 0xffff0000, v53
	v_lshlrev_b32_e32 v40, 16, v54
	v_and_b32_e32 v41, 0xffff0000, v54
	v_lshlrev_b32_e32 v6, 16, v55
	v_and_b32_e32 v7, 0xffff0000, v55
	v_pk_add_f32 v[28:29], v[28:29], v[6:7]
	v_pk_add_f32 v[30:31], v[30:31], v[40:41]
	v_pk_add_f32 v[32:33], v[32:33], v[4:5]
	v_pk_add_f32 v[34:35], v[34:35], v[36:37]
	v_cmp_lt_u32_e32 vcc, 4, v2
	s_and_b64 exec, exec, vcc
	v_lshlrev_b32_e32 v36, 16, v56
	v_and_b32_e32 v37, 0xffff0000, v56
	v_lshlrev_b32_e32 v4, 16, v57
	v_and_b32_e32 v5, 0xffff0000, v57
	v_lshlrev_b32_e32 v40, 16, v58
	v_and_b32_e32 v41, 0xffff0000, v58
	v_lshlrev_b32_e32 v6, 16, v59
	v_and_b32_e32 v7, 0xffff0000, v59
	v_pk_add_f32 v[28:29], v[28:29], v[6:7]
	v_pk_add_f32 v[30:31], v[30:31], v[40:41]
	v_pk_add_f32 v[32:33], v[32:33], v[4:5]
	v_pk_add_f32 v[34:35], v[34:35], v[36:37]
	v_cmp_lt_u32_e32 vcc, 5, v2
	s_and_b64 exec, exec, vcc
	v_lshlrev_b32_e32 v36, 16, v60
	v_and_b32_e32 v37, 0xffff0000, v60
	v_lshlrev_b32_e32 v4, 16, v61
	v_and_b32_e32 v5, 0xffff0000, v61
	v_lshlrev_b32_e32 v40, 16, v62
	v_and_b32_e32 v41, 0xffff0000, v62
	v_lshlrev_b32_e32 v6, 16, v63
	v_and_b32_e32 v7, 0xffff0000, v63
	v_pk_add_f32 v[28:29], v[28:29], v[6:7]
	v_pk_add_f32 v[30:31], v[30:31], v[40:41]
	v_pk_add_f32 v[32:33], v[32:33], v[4:5]
	v_pk_add_f32 v[34:35], v[34:35], v[36:37]
	v_cmp_lt_u32_e32 vcc, 6, v2
	s_and_b64 exec, exec, vcc
	v_lshlrev_b32_e32 v36, 16, v64
	v_and_b32_e32 v37, 0xffff0000, v64
	v_lshlrev_b32_e32 v4, 16, v65
	v_and_b32_e32 v5, 0xffff0000, v65
	v_lshlrev_b32_e32 v40, 16, v66
	v_and_b32_e32 v41, 0xffff0000, v66
	v_lshlrev_b32_e32 v6, 16, v67
	v_and_b32_e32 v7, 0xffff0000, v67
	v_pk_add_f32 v[28:29], v[28:29], v[6:7]
	v_pk_add_f32 v[30:31], v[30:31], v[40:41]
	v_pk_add_f32 v[32:33], v[32:33], v[4:5]
	v_pk_add_f32 v[34:35], v[34:35], v[36:37]
	v_cmp_lt_u32_e32 vcc, 7, v2
	s_and_b64 exec, exec, vcc
	v_lshlrev_b32_e32 v36, 16, v68
	v_and_b32_e32 v37, 0xffff0000, v68
	v_lshlrev_b32_e32 v4, 16, v69
	v_and_b32_e32 v5, 0xffff0000, v69
	v_lshlrev_b32_e32 v40, 16, v70
	v_and_b32_e32 v41, 0xffff0000, v70
	v_lshlrev_b32_e32 v6, 16, v71
	v_and_b32_e32 v7, 0xffff0000, v71
	v_pk_add_f32 v[28:29], v[28:29], v[6:7]
	v_pk_add_f32 v[30:31], v[30:31], v[40:41]
	v_pk_add_f32 v[32:33], v[32:33], v[4:5]
	v_pk_add_f32 v[34:35], v[34:35], v[36:37]
	v_cmp_lt_u32_e32 vcc, 8, v2
	s_and_b64 exec, exec, vcc
	v_lshlrev_b32_e32 v36, 16, v72
	v_and_b32_e32 v37, 0xffff0000, v72
	v_lshlrev_b32_e32 v4, 16, v73
	v_and_b32_e32 v5, 0xffff0000, v73
	v_lshlrev_b32_e32 v40, 16, v74
	v_and_b32_e32 v41, 0xffff0000, v74
	v_lshlrev_b32_e32 v6, 16, v75
	v_and_b32_e32 v7, 0xffff0000, v75
	v_pk_add_f32 v[28:29], v[28:29], v[6:7]
	v_pk_add_f32 v[30:31], v[30:31], v[40:41]
	v_pk_add_f32 v[32:33], v[32:33], v[4:5]
	v_pk_add_f32 v[34:35], v[34:35], v[36:37]
	v_cmp_lt_u32_e32 vcc, 9, v2
	s_and_b64 exec, exec, vcc
	v_lshlrev_b32_e32 v36, 16, v76
	v_and_b32_e32 v37, 0xffff0000, v76
	v_lshlrev_b32_e32 v4, 16, v77
	v_and_b32_e32 v5, 0xffff0000, v77
	v_lshlrev_b32_e32 v40, 16, v78
	v_and_b32_e32 v41, 0xffff0000, v78
	v_lshlrev_b32_e32 v6, 16, v79
	v_and_b32_e32 v7, 0xffff0000, v79
	v_pk_add_f32 v[28:29], v[28:29], v[6:7]
	v_pk_add_f32 v[30:31], v[30:31], v[40:41]
	v_pk_add_f32 v[32:33], v[32:33], v[4:5]
	v_pk_add_f32 v[34:35], v[34:35], v[36:37]
	v_cmp_lt_u32_e32 vcc, 10, v2
	s_and_b64 exec, exec, vcc
	v_lshlrev_b32_e32 v36, 16, v80
	v_and_b32_e32 v37, 0xffff0000, v80
	v_lshlrev_b32_e32 v4, 16, v81
	v_and_b32_e32 v5, 0xffff0000, v81
	v_lshlrev_b32_e32 v40, 16, v82
	v_and_b32_e32 v41, 0xffff0000, v82
	v_lshlrev_b32_e32 v6, 16, v83
	v_and_b32_e32 v7, 0xffff0000, v83
	v_pk_add_f32 v[28:29], v[28:29], v[6:7]
	v_pk_add_f32 v[30:31], v[30:31], v[40:41]
	v_pk_add_f32 v[32:33], v[32:33], v[4:5]
	v_pk_add_f32 v[34:35], v[34:35], v[36:37]
	v_cmp_lt_u32_e32 vcc, 11, v2
	s_and_b64 exec, exec, vcc
	v_lshlrev_b32_e32 v36, 16, v84
	v_and_b32_e32 v37, 0xffff0000, v84
	v_lshlrev_b32_e32 v4, 16, v85
	v_and_b32_e32 v5, 0xffff0000, v85
	v_lshlrev_b32_e32 v40, 16, v86
	v_and_b32_e32 v41, 0xffff0000, v86
	v_lshlrev_b32_e32 v6, 16, v87
	v_and_b32_e32 v7, 0xffff0000, v87
	v_pk_add_f32 v[28:29], v[28:29], v[6:7]
	v_pk_add_f32 v[30:31], v[30:31], v[40:41]
	v_pk_add_f32 v[32:33], v[32:33], v[4:5]
	v_pk_add_f32 v[34:35], v[34:35], v[36:37]
	v_cmp_lt_u32_e32 vcc, 12, v2
	s_and_b64 exec, exec, vcc
	v_lshlrev_b32_e32 v36, 16, v88
	v_and_b32_e32 v37, 0xffff0000, v88
	v_lshlrev_b32_e32 v4, 16, v89
	v_and_b32_e32 v5, 0xffff0000, v89
	v_lshlrev_b32_e32 v40, 16, v90
	v_and_b32_e32 v41, 0xffff0000, v90
	v_lshlrev_b32_e32 v6, 16, v91
	v_and_b32_e32 v7, 0xffff0000, v91
	v_pk_add_f32 v[28:29], v[28:29], v[6:7]
	v_pk_add_f32 v[30:31], v[30:31], v[40:41]
	v_pk_add_f32 v[32:33], v[32:33], v[4:5]
	v_pk_add_f32 v[34:35], v[34:35], v[36:37]
	v_cmp_lt_u32_e32 vcc, 13, v2
	s_and_b64 exec, exec, vcc
	v_lshlrev_b32_e32 v36, 16, v92
	v_and_b32_e32 v37, 0xffff0000, v92
	v_lshlrev_b32_e32 v4, 16, v93
	v_and_b32_e32 v5, 0xffff0000, v93
	v_lshlrev_b32_e32 v40, 16, v94
	v_and_b32_e32 v41, 0xffff0000, v94
	v_lshlrev_b32_e32 v6, 16, v95
	v_and_b32_e32 v7, 0xffff0000, v95
	v_pk_add_f32 v[28:29], v[28:29], v[6:7]
	v_pk_add_f32 v[30:31], v[30:31], v[40:41]
	v_pk_add_f32 v[32:33], v[32:33], v[4:5]
	v_pk_add_f32 v[34:35], v[34:35], v[36:37]
	v_cmp_lt_u32_e32 vcc, 14, v2
	s_and_b64 exec, exec, vcc
	v_lshlrev_b32_e32 v36, 16, v96
	v_and_b32_e32 v37, 0xffff0000, v96
	v_lshlrev_b32_e32 v4, 16, v97
	v_and_b32_e32 v5, 0xffff0000, v97
	v_lshlrev_b32_e32 v40, 16, v98
	v_and_b32_e32 v41, 0xffff0000, v98
	v_lshlrev_b32_e32 v6, 16, v99
	v_and_b32_e32 v7, 0xffff0000, v99
	v_pk_add_f32 v[28:29], v[28:29], v[6:7]
	v_pk_add_f32 v[30:31], v[30:31], v[40:41]
	v_pk_add_f32 v[32:33], v[32:33], v[4:5]
	v_pk_add_f32 v[34:35], v[34:35], v[36:37]
	v_cmp_lt_u32_e32 vcc, 15, v2
	s_and_b64 exec, exec, vcc
	v_lshlrev_b32_e32 v36, 16, v100
	v_and_b32_e32 v37, 0xffff0000, v100
	v_lshlrev_b32_e32 v4, 16, v101
	v_and_b32_e32 v5, 0xffff0000, v101
	v_lshlrev_b32_e32 v40, 16, v102
	v_and_b32_e32 v41, 0xffff0000, v102
	v_lshlrev_b32_e32 v6, 16, v103
	v_and_b32_e32 v7, 0xffff0000, v103
	v_pk_add_f32 v[28:29], v[28:29], v[6:7]
	v_pk_add_f32 v[30:31], v[30:31], v[40:41]
	v_pk_add_f32 v[32:33], v[32:33], v[4:5]
	v_pk_add_f32 v[34:35], v[34:35], v[36:37]
	s_mov_b64 exec, s[6:7]
	s_branch .LBB0_256
